# grid-barrier census: 16 counter loads issued together instead of one round trip each (first barrier only)
# baseline (speedup 1.0000x reference)
; __device__ __forceinline__ unsigned xb_ld(unsigned* p)              { return __hip_atomic_load(p, __ATOMIC_RELAXED, __HIP_MEMORY_SCOPE_AGENT); }
; __device__ __forceinline__ void xcd_barrier_complete(unsigned* bar, unsigned x, unsigned& nloc, unsigned& nx) {
;     ...
;     for (;;) {
;         sum = 0u; cnt = 0u; mine = 0u;
; #pragma unroll
;         for (unsigned j = 0; j < 16; ++j) { const unsigned c = xb_ld(&bar[XB_XCNT(j)]); sum += c; cnt += (c > 0u) ? 1u : 0u; mine = (j == x) ? c : mine; }
;         if (sum == G) break;
;         __builtin_amdgcn_s_sleep(1);
;         if ((++sp & 255u) == 0u) { if (xb_ld(&bar[XB_TMO])) break; if (sp > XB_SPIN_CAP) { atomicAdd(&bar[XB_TMO], 1u); break; } }
;     }
;     nloc = mine > 0u ? mine : 1u; nx = cnt > 0u ? cnt : 1u;
.LBB0_744:
	v_readlane_b32 s6, v251, 38
	v_readlane_b32 s7, v251, 39
	s_mov_b64 s[38:39], -1
	s_mov_b64 s[40:41], -1
	s_nop 2
	global_load_dword v0, v1, s[6:7] sc1
	v_readlane_b32 s6, v251, 40
	v_readlane_b32 s7, v251, 41
	s_waitcnt lgkmcnt(0)
	s_nop 3
	global_load_dword v2, v1, s[6:7] sc1
	v_readlane_b32 s6, v251, 42
	v_readlane_b32 s7, v251, 43
	s_nop 0
	s_nop 0
	s_nop 2
	global_load_dword v3, v1, s[6:7] sc1
	v_readlane_b32 s6, v251, 44
	v_readlane_b32 s7, v251, 45
	s_nop 0
	s_nop 0
	s_nop 2
	global_load_dword v4, v1, s[6:7] sc1
	v_readlane_b32 s6, v251, 46
	v_readlane_b32 s7, v251, 47
	s_nop 0
	s_nop 0
	s_nop 2
	global_load_dword v5, v1, s[6:7] sc1
	v_readlane_b32 s6, v251, 48
	v_readlane_b32 s7, v251, 49
	s_nop 0
	s_nop 0
	s_nop 2
	global_load_dword v6, v1, s[6:7] sc1
	v_readlane_b32 s6, v251, 50
	v_readlane_b32 s7, v251, 51
	s_nop 0
	s_nop 0
	s_nop 2
	global_load_dword v7, v1, s[6:7] sc1
	v_readlane_b32 s6, v251, 52
	v_readlane_b32 s7, v251, 53
	s_nop 0
	s_nop 0
	s_nop 2
	global_load_dword v8, v1, s[6:7] sc1
	v_readlane_b32 s6, v251, 54
	v_readlane_b32 s7, v251, 55
	s_nop 0
	s_nop 0
	s_nop 2
	global_load_dword v9, v1, s[6:7] sc1
	v_readlane_b32 s6, v251, 56
	v_readlane_b32 s7, v251, 57
	s_nop 0
	s_nop 0
	s_nop 2
	global_load_dword v10, v1, s[6:7] sc1
	v_readlane_b32 s6, v251, 58
	v_readlane_b32 s7, v251, 59
	s_nop 0
	s_nop 0
	s_nop 2
	global_load_dword v11, v1, s[6:7] sc1
	v_readlane_b32 s6, v251, 60
	v_readlane_b32 s7, v251, 61
	s_nop 0
	s_nop 0
	s_nop 2
	global_load_dword v12, v1, s[6:7] sc1
	v_readlane_b32 s6, v251, 62
	v_readlane_b32 s7, v251, 63
	s_nop 0
	s_nop 0
	s_nop 2
	global_load_dword v13, v1, s[6:7] sc1
	v_readlane_b32 s6, v252, 0
	v_readlane_b32 s7, v252, 1
	s_nop 0
	s_nop 0
	s_nop 2
	global_load_dword v14, v1, s[6:7] sc1
	v_readlane_b32 s6, v252, 2
	v_readlane_b32 s7, v252, 3
	s_nop 0
	s_nop 0
	s_nop 2
	global_load_dword v15, v1, s[6:7] sc1
	v_readlane_b32 s6, v252, 4
	v_readlane_b32 s7, v252, 5
	s_nop 0
	s_nop 0
	s_nop 2
	global_load_dword v16, v1, s[6:7] sc1
	v_readlane_b32 s6, v253, 49
	s_waitcnt vmcnt(0)
	v_add_u32_e32 v17, v2, v0
	v_add_u32_e32 v17, v17, v3
	v_add_u32_e32 v17, v17, v4
	v_add_u32_e32 v17, v17, v5
	v_add_u32_e32 v17, v17, v6
	v_add_u32_e32 v17, v17, v7
	v_add_u32_e32 v17, v17, v8
	v_add_u32_e32 v17, v17, v9
	v_add_u32_e32 v17, v17, v10
	v_add_u32_e32 v17, v17, v11
	v_add_u32_e32 v17, v17, v12
	v_add_u32_e32 v17, v17, v13
	v_add_u32_e32 v17, v17, v14
	v_add_u32_e32 v17, v17, v15
	v_add_u32_e32 v17, v17, v16
	v_cmp_eq_u32_e32 vcc, s6, v17
	s_cbranch_vccnz .LBB0_743
	s_and_b32 s6, s2, 0xff
	s_cmp_eq_u32 s6, 0
	s_mov_b64 s[34:35], -1
	s_sleep 1
	s_cbranch_scc1 .LBB0_748
	s_and_b64 vcc, exec, s[34:35]
	s_cbranch_vccz .LBB0_743

; __device__ __forceinline__ unsigned xb_ld(unsigned* p)              { return __hip_atomic_load(p, __ATOMIC_RELAXED, __HIP_MEMORY_SCOPE_AGENT); }
; __device__ __forceinline__ void xcd_barrier_complete(unsigned* bar, unsigned x, unsigned& nloc, unsigned& nx) {
;     ...
;     for (;;) {
;         sum = 0u; cnt = 0u; mine = 0u;
; #pragma unroll
;         for (unsigned j = 0; j < 16; ++j) { const unsigned c = xb_ld(&bar[XB_XCNT(j)]); sum += c; cnt += (c > 0u) ? 1u : 0u; mine = (j == x) ? c : mine; }
;         if (sum == G) break;
;         __builtin_amdgcn_s_sleep(1);
;         if ((++sp & 255u) == 0u) { if (xb_ld(&bar[XB_TMO])) break; if (sp > XB_SPIN_CAP) { atomicAdd(&bar[XB_TMO], 1u); break; } }
;     }
;     nloc = mine > 0u ? mine : 1u; nx = cnt > 0u ? cnt : 1u;
.LBB0_822:
	v_readlane_b32 s6, v251, 38
	v_readlane_b32 s7, v251, 39
	s_mov_b64 s[42:43], -1
	s_mov_b64 s[44:45], -1
	s_nop 2
	global_load_dword v0, v1, s[6:7] sc1
	v_readlane_b32 s6, v251, 40
	v_readlane_b32 s7, v251, 41
	s_waitcnt lgkmcnt(0)
	s_nop 3
	global_load_dword v2, v1, s[6:7] sc1
	v_readlane_b32 s6, v251, 42
	v_readlane_b32 s7, v251, 43
	s_nop 0
	s_nop 0
	s_nop 2
	global_load_dword v3, v1, s[6:7] sc1
	v_readlane_b32 s6, v251, 44
	v_readlane_b32 s7, v251, 45
	s_nop 0
	s_nop 0
	s_nop 2
	global_load_dword v4, v1, s[6:7] sc1
	v_readlane_b32 s6, v251, 46
	v_readlane_b32 s7, v251, 47
	s_nop 0
	s_nop 0
	s_nop 2
	global_load_dword v5, v1, s[6:7] sc1
	v_readlane_b32 s6, v251, 48
	v_readlane_b32 s7, v251, 49
	s_nop 0
	s_nop 0
	s_nop 2
	global_load_dword v6, v1, s[6:7] sc1
	v_readlane_b32 s6, v251, 50
	v_readlane_b32 s7, v251, 51
	s_nop 0
	s_nop 0
	s_nop 2
	global_load_dword v7, v1, s[6:7] sc1
	v_readlane_b32 s6, v251, 52
	v_readlane_b32 s7, v251, 53
	s_nop 0
	s_nop 0
	s_nop 2
	global_load_dword v8, v1, s[6:7] sc1
	v_readlane_b32 s6, v251, 54
	v_readlane_b32 s7, v251, 55
	s_nop 0
	s_nop 0
	s_nop 2
	global_load_dword v9, v1, s[6:7] sc1
	v_readlane_b32 s6, v251, 56
	v_readlane_b32 s7, v251, 57
	s_nop 0
	s_nop 0
	s_nop 2
	global_load_dword v10, v1, s[6:7] sc1
	v_readlane_b32 s6, v251, 58
	v_readlane_b32 s7, v251, 59
	s_nop 0
	s_nop 0
	s_nop 2
	global_load_dword v11, v1, s[6:7] sc1
	v_readlane_b32 s6, v251, 60
	v_readlane_b32 s7, v251, 61
	s_nop 0
	s_nop 0
	s_nop 2
	global_load_dword v12, v1, s[6:7] sc1
	v_readlane_b32 s6, v251, 62
	v_readlane_b32 s7, v251, 63
	s_nop 0
	s_nop 0
	s_nop 2
	global_load_dword v13, v1, s[6:7] sc1
	v_readlane_b32 s6, v252, 0
	v_readlane_b32 s7, v252, 1
	s_nop 0
	s_nop 0
	s_nop 2
	global_load_dword v14, v1, s[6:7] sc1
	v_readlane_b32 s6, v252, 2
	v_readlane_b32 s7, v252, 3
	s_nop 0
	s_nop 0
	s_nop 2
	global_load_dword v15, v1, s[6:7] sc1
	v_readlane_b32 s6, v252, 4
	v_readlane_b32 s7, v252, 5
	s_nop 0
	s_nop 0
	s_nop 2
	global_load_dword v16, v1, s[6:7] sc1
	v_readlane_b32 s6, v253, 49
	s_waitcnt vmcnt(0)
	v_add_u32_e32 v17, v2, v0
	v_add_u32_e32 v17, v17, v3
	v_add_u32_e32 v17, v17, v4
	v_add_u32_e32 v17, v17, v5
	v_add_u32_e32 v17, v17, v6
	v_add_u32_e32 v17, v17, v7
	v_add_u32_e32 v17, v17, v8
	v_add_u32_e32 v17, v17, v9
	v_add_u32_e32 v17, v17, v10
	v_add_u32_e32 v17, v17, v11
	v_add_u32_e32 v17, v17, v12
	v_add_u32_e32 v17, v17, v13
	v_add_u32_e32 v17, v17, v14
	v_add_u32_e32 v17, v17, v15
	v_add_u32_e32 v17, v17, v16
	v_cmp_eq_u32_e32 vcc, s6, v17
	s_cbranch_vccnz .LBB0_821
	s_and_b32 s6, s2, 0xff
	s_cmp_eq_u32 s6, 0
	s_mov_b64 s[34:35], -1
	s_sleep 1
	s_cbranch_scc1 .LBB0_826
	s_and_b64 vcc, exec, s[34:35]
	s_cbranch_vccz .LBB0_821

; __device__ __forceinline__ unsigned xb_ld(unsigned* p)              { return __hip_atomic_load(p, __ATOMIC_RELAXED, __HIP_MEMORY_SCOPE_AGENT); }
; __device__ __forceinline__ void xcd_barrier_complete(unsigned* bar, unsigned x, unsigned& nloc, unsigned& nx) {
;     ...
;     for (;;) {
;         sum = 0u; cnt = 0u; mine = 0u;
; #pragma unroll
;         for (unsigned j = 0; j < 16; ++j) { const unsigned c = xb_ld(&bar[XB_XCNT(j)]); sum += c; cnt += (c > 0u) ? 1u : 0u; mine = (j == x) ? c : mine; }
;         if (sum == G) break;
;         __builtin_amdgcn_s_sleep(1);
;         if ((++sp & 255u) == 0u) { if (xb_ld(&bar[XB_TMO])) break; if (sp > XB_SPIN_CAP) { atomicAdd(&bar[XB_TMO], 1u); break; } }
;     }
;     nloc = mine > 0u ? mine : 1u; nx = cnt > 0u ? cnt : 1u;
.LBB0_1752:
	v_readlane_b32 s6, v251, 38
	v_readlane_b32 s7, v251, 39
	s_mov_b64 s[20:21], -1
	s_mov_b64 s[24:25], -1
	s_nop 2
	global_load_dword v0, v1, s[6:7] sc1
	v_readlane_b32 s6, v251, 40
	v_readlane_b32 s7, v251, 41
	s_waitcnt lgkmcnt(0)
	s_nop 3
	global_load_dword v2, v1, s[6:7] sc1
	v_readlane_b32 s6, v251, 42
	v_readlane_b32 s7, v251, 43
	s_nop 0
	s_nop 0
	s_nop 2
	global_load_dword v3, v1, s[6:7] sc1
	v_readlane_b32 s6, v251, 44
	v_readlane_b32 s7, v251, 45
	s_nop 0
	s_nop 0
	s_nop 2
	global_load_dword v4, v1, s[6:7] sc1
	v_readlane_b32 s6, v251, 46
	v_readlane_b32 s7, v251, 47
	s_nop 0
	s_nop 0
	s_nop 2
	global_load_dword v5, v1, s[6:7] sc1
	v_readlane_b32 s6, v251, 48
	v_readlane_b32 s7, v251, 49
	s_nop 0
	s_nop 0
	s_nop 2
	global_load_dword v6, v1, s[6:7] sc1
	v_readlane_b32 s6, v251, 50
	v_readlane_b32 s7, v251, 51
	s_nop 0
	s_nop 0
	s_nop 2
	global_load_dword v7, v1, s[6:7] sc1
	v_readlane_b32 s6, v251, 52
	v_readlane_b32 s7, v251, 53
	s_nop 0
	s_nop 0
	s_nop 2
	global_load_dword v8, v1, s[6:7] sc1
	v_readlane_b32 s6, v251, 54
	v_readlane_b32 s7, v251, 55
	s_nop 0
	s_nop 0
	s_nop 2
	global_load_dword v9, v1, s[6:7] sc1
	v_readlane_b32 s6, v251, 56
	v_readlane_b32 s7, v251, 57
	s_nop 0
	s_nop 0
	s_nop 2
	global_load_dword v10, v1, s[6:7] sc1
	v_readlane_b32 s6, v251, 58
	v_readlane_b32 s7, v251, 59
	s_nop 0
	s_nop 0
	s_nop 2
	global_load_dword v11, v1, s[6:7] sc1
	v_readlane_b32 s6, v251, 60
	v_readlane_b32 s7, v251, 61
	s_nop 0
	s_nop 0
	s_nop 2
	global_load_dword v12, v1, s[6:7] sc1
	v_readlane_b32 s6, v251, 62
	v_readlane_b32 s7, v251, 63
	s_nop 0
	s_nop 0
	s_nop 2
	global_load_dword v13, v1, s[6:7] sc1
	v_readlane_b32 s6, v252, 0
	v_readlane_b32 s7, v252, 1
	s_nop 0
	s_nop 0
	s_nop 2
	global_load_dword v14, v1, s[6:7] sc1
	v_readlane_b32 s6, v252, 2
	v_readlane_b32 s7, v252, 3
	s_nop 0
	s_nop 0
	s_nop 2
	global_load_dword v15, v1, s[6:7] sc1
	v_readlane_b32 s6, v252, 4
	v_readlane_b32 s7, v252, 5
	s_nop 0
	s_nop 0
	s_nop 2
	global_load_dword v16, v1, s[6:7] sc1
	v_readlane_b32 s6, v253, 49
	s_waitcnt vmcnt(0)
	v_add_u32_e32 v17, v2, v0
	v_add_u32_e32 v17, v17, v3
	v_add_u32_e32 v17, v17, v4
	v_add_u32_e32 v17, v17, v5
	v_add_u32_e32 v17, v17, v6
	v_add_u32_e32 v17, v17, v7
	v_add_u32_e32 v17, v17, v8
	v_add_u32_e32 v17, v17, v9
	v_add_u32_e32 v17, v17, v10
	v_add_u32_e32 v17, v17, v11
	v_add_u32_e32 v17, v17, v12
	v_add_u32_e32 v17, v17, v13
	v_add_u32_e32 v17, v17, v14
	v_add_u32_e32 v17, v17, v15
	v_add_u32_e32 v17, v17, v16
	v_cmp_eq_u32_e32 vcc, s6, v17
	s_cbranch_vccnz .LBB0_1751
	s_and_b32 s6, s2, 0xff
	s_cmp_eq_u32 s6, 0
	s_mov_b64 s[30:31], -1
	s_sleep 1
	s_cbranch_scc1 .LBB0_1756
	s_and_b64 vcc, exec, s[30:31]
	s_cbranch_vccz .LBB0_1751
